# P1 row sums without LDS: DPP quad_perm / bank-masked row shifts for xor 1-8, v_readlane of the four row sums for xor 16+32
# speedup vs baseline: 1.0012x; 1.0012x over previous
.LBB0_184:
	s_or_b64 exec, exec, s[4:5]
	s_lshl_b32 s0, s3, 6
	s_lshl_b32 s1, s62, 3
	s_add_i32 s6, s0, s1
	s_ashr_i32 s0, s6, 8
	s_ashr_i32 s1, s0, 31
	s_lshl_b64 s[0:1], s[0:1], 19
	s_add_u32 s5, s52, s0
	s_addc_u32 s4, s53, s1
	s_ashr_i32 s7, s6, 31
	s_lshl_b64 s[0:1], s[6:7], 12
	s_add_u32 s0, s36, s0
	v_ashrrev_i32_e32 v21, 31, v20
	s_addc_u32 s1, s37, s1
	v_lshlrev_b64 v[88:89], 4, v[20:21]
	v_lshl_add_u64 v[0:1], s[0:1], 0, v[88:89]
	s_waitcnt lgkmcnt(0)
	s_barrier
	global_load_dwordx4 v[8:11], v[0:1], off nt
	global_load_dwordx4 v[16:19], v[0:1], off offset:1024 nt
	global_load_dwordx4 v[32:35], v[0:1], off offset:3072 nt
	global_load_dwordx4 v[24:27], v[0:1], off offset:2048 nt
	v_mbcnt_lo_u32_b32 v0, -1, 0
	s_or_b32 s0, s6, 1
	v_mbcnt_hi_u32_b32 v2, -1, v0
	s_ashr_i32 s1, s0, 31
	v_and_b32_e32 v0, 64, v2
	s_lshl_b64 s[0:1], s[0:1], 12
	v_xor_b32_e32 v1, 1, v2
	v_add_u32_e32 v12, 64, v0
	s_add_u32 s0, s36, s0
	v_cmp_lt_i32_e32 vcc, v1, v12
	s_addc_u32 s1, s37, s1
	v_xor_b32_e32 v3, 2, v2
	v_cndmask_b32_e32 v13, v2, v1, vcc
	v_lshl_add_u64 v[0:1], s[0:1], 0, v[88:89]
	global_load_dwordx4 v[52:55], v[0:1], off nt
	global_load_dwordx4 v[40:43], v[0:1], off offset:1024 nt
	global_load_dwordx4 v[48:51], v[0:1], off offset:2048 nt
	global_load_dwordx4 v[36:39], v[0:1], off offset:3072 nt
	v_xor_b32_e32 v4, 4, v2
	v_cmp_lt_i32_e32 vcc, v3, v12
	v_xor_b32_e32 v5, 8, v2
	v_xor_b32_e32 v6, 16, v2
	v_cndmask_b32_e32 v3, v2, v3, vcc
	v_cmp_lt_i32_e32 vcc, v4, v12
	v_xor_b32_e32 v7, 32, v2
	v_lshlrev_b32_e32 v109, 2, v3
	v_cndmask_b32_e32 v4, v2, v4, vcc
	v_cmp_lt_i32_e32 vcc, v5, v12
	v_lshlrev_b32_e32 v108, 2, v4
	v_lshlrev_b32_e32 v110, 2, v13
	v_cndmask_b32_e32 v5, v2, v5, vcc
	v_cmp_lt_i32_e32 vcc, v6, v12
	v_lshlrev_b32_e32 v107, 2, v5
	s_or_b32 s0, s6, 2
	v_cndmask_b32_e32 v6, v2, v6, vcc
	v_cmp_lt_i32_e32 vcc, v7, v12
	v_lshlrev_b32_e32 v106, 2, v6
	s_ashr_i32 s1, s0, 31
	v_cndmask_b32_e32 v2, v2, v7, vcc
	v_lshlrev_b32_e32 v105, 2, v2
	s_lshl_b64 s[0:1], s[0:1], 12
	s_add_u32 s0, s36, s0
	s_addc_u32 s1, s37, s1
	v_mov_b32_e32 v104, 0x358637bd
	s_mov_b32 s3, 0xf800000
	s_or_b32 s8, s6, 3
	s_ashr_i32 s9, s8, 31
	v_mov_b32_e32 v111, 0x260
	v_lshl_add_u32 v30, v20, 4, 0
	v_lshlrev_b32_e32 v85, 8, v20
	v_and_b32_e32 v84, 15, v20
	s_waitcnt vmcnt(7)
	v_pk_mul_f32 v[0:1], v[10:11], v[10:11]
	v_pk_mul_f32 v[2:3], v[8:9], v[8:9]
	s_waitcnt vmcnt(6)
	v_pk_mul_f32 v[4:5], v[18:19], v[18:19]
	v_pk_mul_f32 v[6:7], v[16:17], v[16:17]
	v_pk_mov_b32 v[22:23], v[2:3], v[0:1] op_sel:[1,0]
	v_mov_b32_e32 v3, v1
	v_pk_mov_b32 v[0:1], v[6:7], v[4:5] op_sel:[1,0]
	v_mov_b32_e32 v7, v5
	s_waitcnt vmcnt(5)
	v_mul_f32_e32 v15, v32, v32
	s_waitcnt vmcnt(4)
	v_mul_f32_e32 v12, v25, v25
	v_mul_f32_e32 v14, v27, v27
	v_pk_add_f32 v[2:3], v[22:23], v[2:3]
	v_pk_add_f32 v[0:1], v[0:1], v[6:7]
	v_mul_f32_e32 v21, v33, v33
	v_mul_f32_e32 v28, v34, v34
	v_mul_f32_e32 v29, v35, v35
	v_pk_fma_f32 v[4:5], v[24:25], v[24:25], v[12:13] op_sel_hi:[1,1,0]
	v_pk_fma_f32 v[12:13], v[26:27], v[26:27], v[14:15] op_sel_hi:[1,1,0]
	v_pk_add_f32 v[2:3], v[2:3], v[2:3] op_sel:[0,1] op_sel_hi:[1,0]
	v_pk_add_f32 v[0:1], v[0:1], v[0:1] op_sel:[0,1] op_sel_hi:[1,0]
	v_mov_b32_e32 v5, v28
	v_mov_b32_e32 v13, v29
	v_mov_b32_e32 v3, v15
	v_mov_b32_e32 v1, v21
	v_pk_add_f32 v[4:5], v[4:5], v[12:13]
	v_pk_add_f32 v[0:1], v[2:3], v[0:1]
	s_nop 0
	v_pk_add_f32 v[0:1], v[0:1], v[4:5]
	s_waitcnt vmcnt(3)
	v_pk_mul_f32 v[4:5], v[52:53], v[52:53]
	v_add_f32_e32 v2, v0, v1
	v_lshl_add_u64 v[0:1], s[0:1], 0, v[88:89]
	global_load_dwordx4 v[64:67], v[0:1], off nt
	global_load_dwordx4 v[60:63], v[0:1], off offset:1024 nt
	global_load_dwordx4 v[56:59], v[0:1], off offset:2048 nt
	global_load_dwordx4 v[44:47], v[0:1], off offset:3072 nt
	s_lshl_b64 s[0:1], s[8:9], 12
	s_waitcnt lgkmcnt(0)
	s_nop 1
	v_add_f32_dpp v2, v2, v2 quad_perm:[1,0,3,2] row_mask:0xf bank_mask:0xf
	s_add_u32 s0, s36, s0
	s_addc_u32 s1, s37, s1
	s_lshl_b32 s7, s6, 7
	v_lshl_add_u64 v[0:1], s[0:1], 0, v[88:89]
	s_waitcnt lgkmcnt(0)
	s_nop 1
	v_add_f32_dpp v2, v2, v2 quad_perm:[2,3,0,1] row_mask:0xf bank_mask:0xf
	s_and_b32 s7, s7, 0x7c00
	global_load_dwordx4 v[76:79], v[0:1], off nt
	global_load_dwordx4 v[68:71], v[0:1], off offset:1024 nt
	s_add_u32 s10, s5, s7
	s_addc_u32 s11, s4, 0
	s_waitcnt lgkmcnt(0)
	s_nop 1
	v_mov_b32_dpp v3, v2 row_shl:4 row_mask:0xf bank_mask:0x5
	v_mov_b32_dpp v3, v2 row_shr:4 row_mask:0xf bank_mask:0xa
	v_add_f32_e32 v2, v2, v3
	s_or_b32 s0, s6, 4
	s_ashr_i32 s1, s0, 31
	s_lshl_b64 s[0:1], s[0:1], 12
	global_load_dwordx4 v[80:83], v[0:1], off offset:2048 nt
	global_load_dwordx4 v[72:75], v[0:1], off offset:3072 nt
	s_waitcnt lgkmcnt(0)
	s_nop 1
	v_mov_b32_dpp v3, v2 row_shl:8 row_mask:0xf bank_mask:0x3
	v_mov_b32_dpp v3, v2 row_shr:8 row_mask:0xf bank_mask:0xc
	v_add_f32_e32 v6, v2, v3
	v_pk_mul_f32 v[2:3], v[54:55], v[54:55]
	s_add_u32 s8, s36, s0
	v_pk_mov_b32 v[12:13], v[4:5], v[2:3] op_sel:[1,0]
	v_mov_b32_e32 v5, v3
	s_waitcnt lgkmcnt(0)
	s_nop 1
	v_readlane_b32 s98, v6, 0
	v_readlane_b32 s99, v6, 16
	v_readlane_b32 s100, v6, 32
	v_readlane_b32 s101, v6, 48
	s_nop 1
	v_mov_b32_e32 v7, s99
	v_add_f32_e32 v7, s98, v7
	v_mov_b32_e32 v14, s101
	v_add_f32_e32 v14, s100, v14
	v_add_f32_e32 v14, v7, v14
	v_pk_add_f32 v[2:3], v[12:13], v[4:5]
	s_waitcnt vmcnt(10)
	v_pk_mul_f32 v[6:7], v[42:43], v[42:43]
	v_pk_add_f32 v[2:3], v[2:3], v[2:3] op_sel:[0,1] op_sel_hi:[1,0]
	s_addc_u32 s9, s37, s1
	s_waitcnt lgkmcnt(0)
	v_mov_b32_e32 v4, v14
	v_fmamk_f32 v4, v4, 0x3a800000, v104
	v_mul_f32_e32 v5, 0x4f800000, v4
	v_cmp_gt_f32_e32 vcc, s3, v4
	s_nop 1
	v_cndmask_b32_e32 v14, v4, v5, vcc
	v_pk_mul_f32 v[4:5], v[40:41], v[40:41]
	v_sqrt_f32_e32 v15, v14
	v_pk_mov_b32 v[12:13], v[4:5], v[6:7] op_sel:[1,0]
	v_mov_b32_e32 v5, v7
	v_pk_add_f32 v[4:5], v[12:13], v[4:5]
	s_waitcnt vmcnt(8)
	v_mul_f32_e32 v6, v36, v36
	v_mul_f32_e32 v7, v37, v37
	v_pk_add_f32 v[4:5], v[4:5], v[4:5] op_sel:[0,1] op_sel_hi:[1,0]
	v_mov_b32_e32 v3, v6
	v_mov_b32_e32 v5, v7
	v_pk_add_f32 v[2:3], v[2:3], v[4:5]
	v_mul_f32_e32 v4, v49, v49
	v_mul_f32_e32 v6, v51, v51
	v_mul_f32_e32 v12, v38, v38
	v_mul_f32_e32 v13, v39, v39
	v_pk_fma_f32 v[4:5], v[48:49], v[48:49], v[4:5] op_sel_hi:[1,1,0]
	v_pk_fma_f32 v[6:7], v[50:51], v[50:51], v[6:7] op_sel_hi:[1,1,0]
	v_mov_b32_e32 v5, v12
	v_mov_b32_e32 v7, v13
	v_pk_add_f32 v[4:5], v[4:5], v[6:7]
	s_nop 0
	v_pk_add_f32 v[2:3], v[2:3], v[4:5]
	v_add_u32_e32 v4, -1, v15
	v_add_f32_e32 v2, v2, v3
	v_fma_f32 v5, -v4, v15, v14
	v_cmp_ge_f32_e64 s[0:1], 0, v5
	v_add_u32_e32 v5, 1, v15
	v_fma_f32 v6, -v5, v15, v14
	s_waitcnt lgkmcnt(0)
	s_nop 1
	v_add_f32_dpp v2, v2, v2 quad_perm:[1,0,3,2] row_mask:0xf bank_mask:0xf
	v_cndmask_b32_e64 v4, v15, v4, s[0:1]
	v_cmp_lt_f32_e64 s[0:1], 0, v6
	s_waitcnt lgkmcnt(0)
	s_nop 1
	v_add_f32_dpp v2, v2, v2 quad_perm:[2,3,0,1] row_mask:0xf bank_mask:0xf
	v_cndmask_b32_e64 v4, v4, v5, s[0:1]
	v_mul_f32_e32 v5, 0x37800000, v4
	v_cndmask_b32_e32 v4, v4, v5, vcc
	v_cmp_class_f32_e32 vcc, v14, v111
	s_waitcnt lgkmcnt(0)
	s_nop 1
	v_mov_b32_dpp v3, v2 row_shl:4 row_mask:0xf bank_mask:0x5
	v_mov_b32_dpp v3, v2 row_shr:4 row_mask:0xf bank_mask:0xa
	v_add_f32_e32 v2, v2, v3
	v_cndmask_b32_e32 v12, v4, v14, vcc
	v_div_scale_f32 v13, s[0:1], v12, v12, 1.0
	v_rcp_f32_e32 v14, v13
	s_waitcnt lgkmcnt(0)
	s_nop 1
	v_mov_b32_dpp v3, v2 row_shl:8 row_mask:0xf bank_mask:0x3
	v_mov_b32_dpp v3, v2 row_shr:8 row_mask:0xf bank_mask:0xc
	v_add_f32_e32 v2, v2, v3
	v_div_scale_f32 v15, vcc, 1.0, v12, 1.0
	v_fma_f32 v0, -v13, v14, 1.0
	v_fmac_f32_e32 v14, v0, v14
	s_waitcnt lgkmcnt(0)
	s_nop 1
	v_readlane_b32 s98, v2, 0
	v_readlane_b32 s99, v2, 16
	v_readlane_b32 s100, v2, 32
	v_readlane_b32 s101, v2, 48
	s_nop 1
	v_mov_b32_e32 v3, s99
	v_add_f32_e32 v3, s98, v3
	v_mov_b32_e32 v0, s101
	v_add_f32_e32 v0, s100, v0
	v_add_f32_e32 v0, v3, v0
	s_waitcnt vmcnt(7)
	v_pk_mul_f32 v[2:3], v[64:65], v[64:65]
	v_mul_f32_e32 v21, v15, v14
	v_fma_f32 v22, -v13, v21, v15
	v_fmac_f32_e32 v21, v22, v14
	s_waitcnt lgkmcnt(0)
	v_mov_b32_e32 v0, v0
	v_fmamk_f32 v0, v0, 0x3a800000, v104
	v_mul_f32_e32 v1, 0x4f800000, v0
	v_cmp_gt_f32_e64 s[0:1], s3, v0
	s_nop 1
	v_cndmask_b32_e64 v23, v0, v1, s[0:1]
	v_pk_mul_f32 v[0:1], v[66:67], v[66:67]
	v_sqrt_f32_e32 v28, v23
	v_pk_mov_b32 v[4:5], v[2:3], v[0:1] op_sel:[1,0]
	v_mov_b32_e32 v3, v1
	v_pk_add_f32 v[0:1], v[4:5], v[2:3]
	s_waitcnt vmcnt(6)
	v_pk_mul_f32 v[2:3], v[62:63], v[62:63]
	v_pk_mul_f32 v[4:5], v[60:61], v[60:61]
	v_pk_add_f32 v[0:1], v[0:1], v[0:1] op_sel:[0,1] op_sel_hi:[1,0]
	v_pk_mov_b32 v[6:7], v[4:5], v[2:3] op_sel:[1,0]
	v_mov_b32_e32 v5, v3
	v_pk_add_f32 v[2:3], v[6:7], v[4:5]
	s_waitcnt vmcnt(4)
	v_mul_f32_e32 v4, v44, v44
	v_mul_f32_e32 v5, v45, v45
	v_pk_add_f32 v[2:3], v[2:3], v[2:3] op_sel:[0,1] op_sel_hi:[1,0]
	v_mov_b32_e32 v1, v4
	v_mov_b32_e32 v3, v5
	v_pk_add_f32 v[0:1], v[0:1], v[2:3]
	v_mul_f32_e32 v2, v57, v57
	v_mul_f32_e32 v4, v59, v59
	v_mul_f32_e32 v6, v46, v46
	v_mul_f32_e32 v7, v47, v47
	v_pk_fma_f32 v[2:3], v[56:57], v[56:57], v[2:3] op_sel_hi:[1,1,0]
	v_pk_fma_f32 v[4:5], v[58:59], v[58:59], v[4:5] op_sel_hi:[1,1,0]
	v_mov_b32_e32 v3, v6
	v_mov_b32_e32 v5, v7
	v_pk_add_f32 v[2:3], v[2:3], v[4:5]
	s_nop 0
	v_pk_add_f32 v[0:1], v[0:1], v[2:3]
	v_add_u32_e32 v3, -1, v28
	v_add_f32_e32 v0, v0, v1
	v_fma_f32 v4, -v3, v28, v23
	v_cmp_ge_f32_e64 s[4:5], 0, v4
	v_add_u32_e32 v4, 1, v28
	v_fma_f32 v5, -v4, v28, v23
	s_waitcnt lgkmcnt(0)
	s_nop 1
	v_add_f32_dpp v0, v0, v0 quad_perm:[1,0,3,2] row_mask:0xf bank_mask:0xf
	v_cndmask_b32_e64 v3, v28, v3, s[4:5]
	v_cmp_lt_f32_e64 s[4:5], 0, v5
	v_fma_f32 v2, -v13, v21, v15
	v_div_fmas_f32 v2, v2, v14, v21
	s_waitcnt lgkmcnt(0)
	s_nop 1
	v_add_f32_dpp v0, v0, v0 quad_perm:[2,3,0,1] row_mask:0xf bank_mask:0xf
	v_cndmask_b32_e64 v3, v3, v4, s[4:5]
	v_mul_f32_e32 v4, 0x37800000, v3
	v_cndmask_b32_e64 v3, v3, v4, s[0:1]
	v_cmp_class_f32_e64 s[0:1], v23, v111
	s_waitcnt lgkmcnt(0)
	s_nop 1
	v_mov_b32_dpp v1, v0 row_shl:4 row_mask:0xf bank_mask:0x5
	v_mov_b32_dpp v1, v0 row_shr:4 row_mask:0xf bank_mask:0xa
	v_add_f32_e32 v0, v0, v1
	v_cndmask_b32_e64 v13, v3, v23, s[0:1]
	v_div_scale_f32 v15, s[0:1], v13, v13, 1.0
	v_rcp_f32_e32 v22, v15
	s_waitcnt lgkmcnt(0)
	s_nop 1
	v_mov_b32_dpp v1, v0 row_shl:8 row_mask:0xf bank_mask:0x3
	v_mov_b32_dpp v1, v0 row_shr:8 row_mask:0xf bank_mask:0xc
	v_add_f32_e32 v0, v0, v1
	v_div_fixup_f32 v86, v2, v12, 1.0
	v_fma_f32 v2, -v15, v22, 1.0
	v_fmac_f32_e32 v22, v2, v22
	s_waitcnt vmcnt(3)
	v_pk_mul_f32 v[2:3], v[76:77], v[76:77]
	s_waitcnt lgkmcnt(0)
	s_nop 1
	v_readlane_b32 s98, v0, 0
	v_readlane_b32 s99, v0, 16
	v_readlane_b32 s100, v0, 32
	v_readlane_b32 s101, v0, 48
	s_nop 1
	v_mov_b32_e32 v1, s99
	v_add_f32_e32 v1, s98, v1
	v_mov_b32_e32 v0, s101
	v_add_f32_e32 v0, s100, v0
	v_add_f32_e32 v0, v1, v0
	v_div_scale_f32 v12, vcc, 1.0, v13, 1.0
	v_mul_f32_e32 v14, v12, v22
	v_fma_f32 v21, -v15, v14, v12
	s_waitcnt lgkmcnt(0)
	v_mov_b32_e32 v0, v0
	v_fmamk_f32 v0, v0, 0x3a800000, v104
	v_mul_f32_e32 v1, 0x4f800000, v0
	v_cmp_gt_f32_e64 s[0:1], s3, v0
	v_fmac_f32_e32 v14, v21, v22
	v_pk_mul_f32 v[16:17], v[16:17], v[86:87] op_sel_hi:[1,0]
	v_cndmask_b32_e64 v23, v0, v1, s[0:1]
	v_pk_mul_f32 v[0:1], v[78:79], v[78:79]
	v_sqrt_f32_e32 v28, v23
	v_pk_mov_b32 v[4:5], v[2:3], v[0:1] op_sel:[1,0]
	v_mov_b32_e32 v3, v1
	v_pk_add_f32 v[0:1], v[4:5], v[2:3]
	s_waitcnt vmcnt(2)
	v_pk_mul_f32 v[2:3], v[70:71], v[70:71]
	v_pk_mul_f32 v[4:5], v[68:69], v[68:69]
	v_pk_add_f32 v[0:1], v[0:1], v[0:1] op_sel:[0,1] op_sel_hi:[1,0]
	v_pk_mov_b32 v[6:7], v[4:5], v[2:3] op_sel:[1,0]
	v_mov_b32_e32 v5, v3
	v_pk_add_f32 v[2:3], v[6:7], v[4:5]
	s_waitcnt vmcnt(0)
	v_mul_f32_e32 v4, v72, v72
	v_mul_f32_e32 v5, v73, v73
	v_pk_add_f32 v[2:3], v[2:3], v[2:3] op_sel:[0,1] op_sel_hi:[1,0]
	v_mov_b32_e32 v1, v4
	v_mov_b32_e32 v3, v5
	v_pk_add_f32 v[0:1], v[0:1], v[2:3]
	v_mul_f32_e32 v2, v81, v81
	v_mul_f32_e32 v4, v83, v83
	v_mul_f32_e32 v6, v74, v74
	v_mul_f32_e32 v7, v75, v75
	v_pk_fma_f32 v[2:3], v[80:81], v[80:81], v[2:3] op_sel_hi:[1,1,0]
	v_pk_fma_f32 v[4:5], v[82:83], v[82:83], v[4:5] op_sel_hi:[1,1,0]
	v_mov_b32_e32 v3, v6
	v_mov_b32_e32 v5, v7
	v_pk_add_f32 v[2:3], v[2:3], v[4:5]
	v_pk_mul_f32 v[18:19], v[18:19], v[86:87] op_sel_hi:[1,0]
	v_pk_add_f32 v[0:1], v[0:1], v[2:3]
	v_add_u32_e32 v3, -1, v28
	v_add_f32_e32 v0, v0, v1
	v_fma_f32 v4, -v3, v28, v23
	v_cmp_ge_f32_e64 s[4:5], 0, v4
	v_add_u32_e32 v4, 1, v28
	v_fma_f32 v5, -v4, v28, v23
	s_waitcnt lgkmcnt(0)
	s_nop 1
	v_add_f32_dpp v0, v0, v0 quad_perm:[1,0,3,2] row_mask:0xf bank_mask:0xf
	v_cndmask_b32_e64 v3, v28, v3, s[4:5]
	v_cmp_lt_f32_e64 s[4:5], 0, v5
	v_fma_f32 v2, -v15, v14, v12
	v_div_fmas_f32 v2, v2, v22, v14
	s_waitcnt lgkmcnt(0)
	s_nop 1
	v_add_f32_dpp v0, v0, v0 quad_perm:[2,3,0,1] row_mask:0xf bank_mask:0xf
	v_cndmask_b32_e64 v3, v3, v4, s[4:5]
	v_mul_f32_e32 v4, 0x37800000, v3
	v_cndmask_b32_e64 v3, v3, v4, s[0:1]
	v_cmp_class_f32_e64 s[0:1], v23, v111
	s_waitcnt lgkmcnt(0)
	s_nop 1
	v_mov_b32_dpp v1, v0 row_shl:4 row_mask:0xf bank_mask:0x5
	v_mov_b32_dpp v1, v0 row_shr:4 row_mask:0xf bank_mask:0xa
	v_add_f32_e32 v0, v0, v1
	v_cndmask_b32_e64 v3, v3, v23, s[0:1]
	v_div_scale_f32 v4, s[0:1], v3, v3, 1.0
	v_rcp_f32_e32 v5, v4
	s_waitcnt lgkmcnt(0)
	s_nop 1
	v_mov_b32_dpp v1, v0 row_shl:8 row_mask:0xf bank_mask:0x3
	v_mov_b32_dpp v1, v0 row_shr:8 row_mask:0xf bank_mask:0xc
	v_add_f32_e32 v0, v0, v1
	v_div_fixup_f32 v90, v2, v13, 1.0
	v_fma_f32 v2, -v4, v5, 1.0
	v_fmac_f32_e32 v5, v2, v5
	v_div_scale_f32 v2, vcc, 1.0, v3, 1.0
	s_waitcnt lgkmcnt(0)
	s_nop 1
	v_readlane_b32 s98, v0, 0
	v_readlane_b32 s99, v0, 16
	v_readlane_b32 s100, v0, 32
	v_readlane_b32 s101, v0, 48
	s_nop 1
	v_mov_b32_e32 v1, s99
	v_add_f32_e32 v1, s98, v1
	v_mov_b32_e32 v0, s101
	v_add_f32_e32 v0, s100, v0
	v_add_f32_e32 v0, v1, v0
	v_mul_f32_e32 v6, v2, v5
	v_fma_f32 v7, -v4, v6, v2
	v_fmac_f32_e32 v6, v7, v5
	v_fma_f32 v2, -v4, v6, v2
	s_waitcnt lgkmcnt(0)
	v_mov_b32_e32 v0, v0
	v_fmamk_f32 v0, v0, 0x3a800000, v104
	v_mul_f32_e32 v1, 0x4f800000, v0
	v_cmp_gt_f32_e64 s[0:1], s3, v0
	v_div_fmas_f32 v2, v2, v5, v6
	v_div_fixup_f32 v92, v2, v3, 1.0
	v_cndmask_b32_e64 v0, v0, v1, s[0:1]
	v_sqrt_f32_e32 v1, v0
	v_pk_mul_f32 v[22:23], v[8:9], v[86:87] op_sel_hi:[1,0]
	v_pk_mul_f32 v[28:29], v[10:11], v[86:87] op_sel_hi:[1,0]
	v_pk_mul_f32 v[100:101], v[24:25], v[86:87] op_sel_hi:[1,0]
	v_add_u32_e32 v4, -1, v1
	v_fma_f32 v7, -v4, v1, v0
	v_cmp_ge_f32_e64 s[4:5], 0, v7
	v_add_u32_e32 v7, 1, v1
	v_pk_mul_f32 v[102:103], v[26:27], v[86:87] op_sel_hi:[1,0]
	v_cndmask_b32_e64 v4, v1, v4, s[4:5]
	v_fma_f32 v1, -v7, v1, v0
	v_cmp_lt_f32_e64 s[4:5], 0, v1
	v_add_u32_e32 v87, 0x8000, v85
	v_pk_mul_f32 v[32:33], v[32:33], v[86:87] op_sel_hi:[1,0]
	v_cndmask_b32_e64 v1, v4, v7, s[4:5]
	v_mul_f32_e32 v4, 0x37800000, v1
	v_cndmask_b32_e64 v1, v1, v4, s[0:1]
	v_cmp_class_f32_e64 s[0:1], v0, v111
	v_pk_mul_f32 v[34:35], v[34:35], v[86:87] op_sel_hi:[1,0]
	s_nop 0
	v_cndmask_b32_e64 v0, v1, v0, s[0:1]
	v_div_scale_f32 v1, s[0:1], v0, v0, 1.0
	v_rcp_f32_e32 v4, v1
	s_movk_i32 s0, 0xf000
	v_and_or_b32 v20, v85, s0, v84
	v_ashrrev_i32_e32 v21, 31, v20
	v_fma_f32 v2, -v1, v4, 1.0
	v_fmac_f32_e32 v4, v2, v4
	v_div_scale_f32 v2, vcc, 1.0, v0, 1.0
	v_mul_f32_e32 v3, v2, v4
	v_fma_f32 v5, -v1, v3, v2
	v_fmac_f32_e32 v3, v5, v4
	v_fma_f32 v1, -v1, v3, v2
	v_div_fmas_f32 v1, v1, v4, v3
	v_div_fixup_f32 v94, v1, v0, 1.0
	ds_read_b128 v[0:3], v30
	ds_read_b128 v[4:7], v30 offset:4096
	ds_read_b128 v[8:11], v30 offset:1024
	ds_read_b128 v[12:15], v30 offset:5120
	v_lshl_add_u64 v[96:97], v[20:21], 3, s[10:11]
	s_waitcnt lgkmcnt(0)
	v_pk_fma_f32 v[28:29], v[28:29], v[2:3], v[6:7]
	s_waitcnt lgkmcnt(0)
	v_pk_fma_f32 v[18:19], v[18:19], v[10:11], v[14:15]
	v_pk_fma_f32 v[16:17], v[16:17], v[8:9], v[12:13]
	v_pk_fma_f32 v[22:23], v[22:23], v[0:1], v[4:5]
	v_cvt_pk_bf16_f32 v16, v16, v17
	v_cvt_pk_bf16_f32 v17, v18, v19
	v_add_u32_e32 v18, 0x4000, v85
	v_and_or_b32 v18, v18, s0, v84
	v_ashrrev_i32_e32 v19, 31, v18
	v_cvt_pk_bf16_f32 v22, v22, v23
	v_cvt_pk_bf16_f32 v23, v28, v29
	v_lshl_add_u64 v[98:99], v[18:19], 3, s[10:11]
	global_store_dwordx2 v[96:97], v[22:23], off
	global_store_dwordx2 v[98:99], v[16:17], off
	ds_read_b128 v[16:19], v30 offset:2048
	ds_read_b128 v[20:23], v30 offset:6144
	ds_read_b128 v[24:27], v30 offset:3072
	ds_read_b128 v[28:31], v30 offset:7168
	s_waitcnt lgkmcnt(0)
	v_pk_fma_f32 v[100:101], v[100:101], v[16:17], v[20:21]
	s_waitcnt lgkmcnt(0)
	v_pk_fma_f32 v[34:35], v[34:35], v[26:27], v[30:31]
	v_pk_fma_f32 v[32:33], v[32:33], v[24:25], v[28:29]
	v_cvt_pk_bf16_f32 v112, v100, v101
	v_cvt_pk_bf16_f32 v32, v32, v33
	v_cvt_pk_bf16_f32 v33, v34, v35
	v_add_u32_e32 v34, 0xc000, v85
	v_and_or_b32 v100, v87, s0, v84
	v_and_or_b32 v34, v34, s0, v84
	v_pk_fma_f32 v[102:103], v[102:103], v[18:19], v[22:23]
	v_ashrrev_i32_e32 v101, 31, v100
	v_ashrrev_i32_e32 v35, 31, v34
	v_cvt_pk_bf16_f32 v113, v102, v103
	v_lshl_add_u64 v[100:101], v[100:101], 3, s[10:11]
	v_lshl_add_u64 v[102:103], v[34:35], 3, s[10:11]
	global_store_dwordx2 v[100:101], v[112:113], off
	global_store_dwordx2 v[102:103], v[32:33], off
	v_pk_mul_f32 v[32:33], v[52:53], v[90:91] op_sel_hi:[1,0]
	v_pk_mul_f32 v[34:35], v[54:55], v[90:91] op_sel_hi:[1,0]
	v_pk_fma_f32 v[32:33], v[32:33], v[0:1], v[4:5]
	v_pk_fma_f32 v[34:35], v[34:35], v[2:3], v[6:7]
	v_cvt_pk_bf16_f32 v32, v32, v33
	v_cvt_pk_bf16_f32 v33, v34, v35
	global_store_dwordx2 v[96:97], v[32:33], off offset:128
	v_pk_mul_f32 v[32:33], v[40:41], v[90:91] op_sel_hi:[1,0]
	v_pk_mul_f32 v[34:35], v[42:43], v[90:91] op_sel_hi:[1,0]
	v_pk_fma_f32 v[32:33], v[32:33], v[8:9], v[12:13]
	v_pk_fma_f32 v[34:35], v[34:35], v[10:11], v[14:15]
	v_cvt_pk_bf16_f32 v32, v32, v33
	v_cvt_pk_bf16_f32 v33, v34, v35
	global_store_dwordx2 v[98:99], v[32:33], off offset:128
	v_pk_mul_f32 v[32:33], v[48:49], v[90:91] op_sel_hi:[1,0]
	v_pk_mul_f32 v[34:35], v[50:51], v[90:91] op_sel_hi:[1,0]
	v_pk_fma_f32 v[32:33], v[32:33], v[16:17], v[20:21]
	v_pk_fma_f32 v[34:35], v[34:35], v[18:19], v[22:23]
	v_cvt_pk_bf16_f32 v32, v32, v33
	v_cvt_pk_bf16_f32 v33, v34, v35
	global_store_dwordx2 v[100:101], v[32:33], off offset:128
	v_pk_mul_f32 v[32:33], v[36:37], v[90:91] op_sel_hi:[1,0]
	v_pk_mul_f32 v[34:35], v[38:39], v[90:91] op_sel_hi:[1,0]
	v_pk_fma_f32 v[32:33], v[32:33], v[24:25], v[28:29]
	v_pk_fma_f32 v[34:35], v[34:35], v[26:27], v[30:31]
	v_cvt_pk_bf16_f32 v32, v32, v33
	v_cvt_pk_bf16_f32 v33, v34, v35
	global_store_dwordx2 v[102:103], v[32:33], off offset:128
	v_pk_mul_f32 v[32:33], v[64:65], v[92:93] op_sel_hi:[1,0]
	v_pk_mul_f32 v[34:35], v[66:67], v[92:93] op_sel_hi:[1,0]
	v_pk_fma_f32 v[32:33], v[0:1], v[32:33], v[4:5]
	v_pk_fma_f32 v[34:35], v[2:3], v[34:35], v[6:7]
	v_cvt_pk_bf16_f32 v32, v32, v33
	v_cvt_pk_bf16_f32 v33, v34, v35
	global_store_dwordx2 v[96:97], v[32:33], off offset:256
	v_pk_mul_f32 v[32:33], v[60:61], v[92:93] op_sel_hi:[1,0]
	v_pk_mul_f32 v[34:35], v[62:63], v[92:93] op_sel_hi:[1,0]
	v_pk_fma_f32 v[32:33], v[32:33], v[8:9], v[12:13]
	v_pk_fma_f32 v[34:35], v[34:35], v[10:11], v[14:15]
	v_cvt_pk_bf16_f32 v32, v32, v33
	v_cvt_pk_bf16_f32 v33, v34, v35
	global_store_dwordx2 v[98:99], v[32:33], off offset:256
	v_pk_mul_f32 v[32:33], v[56:57], v[92:93] op_sel_hi:[1,0]
	v_pk_mul_f32 v[34:35], v[58:59], v[92:93] op_sel_hi:[1,0]
	v_pk_fma_f32 v[32:33], v[32:33], v[16:17], v[20:21]
	v_pk_fma_f32 v[34:35], v[34:35], v[18:19], v[22:23]
	v_cvt_pk_bf16_f32 v32, v32, v33
	v_cvt_pk_bf16_f32 v33, v34, v35
	global_store_dwordx2 v[100:101], v[32:33], off offset:256
	v_pk_mul_f32 v[32:33], v[44:45], v[92:93] op_sel_hi:[1,0]
	v_pk_mul_f32 v[34:35], v[46:47], v[92:93] op_sel_hi:[1,0]
	v_pk_fma_f32 v[32:33], v[32:33], v[24:25], v[28:29]
	v_pk_fma_f32 v[34:35], v[34:35], v[26:27], v[30:31]
	v_cvt_pk_bf16_f32 v32, v32, v33
	v_cvt_pk_bf16_f32 v33, v34, v35
	global_store_dwordx2 v[102:103], v[32:33], off offset:256
	v_pk_mul_f32 v[32:33], v[76:77], v[94:95] op_sel_hi:[1,0]
	v_pk_mul_f32 v[34:35], v[78:79], v[94:95] op_sel_hi:[1,0]
	v_pk_fma_f32 v[32:33], v[0:1], v[32:33], v[4:5]
	v_pk_fma_f32 v[34:35], v[2:3], v[34:35], v[6:7]
	v_cvt_pk_bf16_f32 v32, v32, v33
	v_cvt_pk_bf16_f32 v33, v34, v35
	global_store_dwordx2 v[96:97], v[32:33], off offset:384
	v_pk_mul_f32 v[32:33], v[68:69], v[94:95] op_sel_hi:[1,0]
	v_pk_mul_f32 v[34:35], v[70:71], v[94:95] op_sel_hi:[1,0]
	v_pk_fma_f32 v[32:33], v[8:9], v[32:33], v[12:13]
	v_pk_fma_f32 v[34:35], v[10:11], v[34:35], v[14:15]
	v_cvt_pk_bf16_f32 v32, v32, v33
	v_cvt_pk_bf16_f32 v33, v34, v35
	global_store_dwordx2 v[98:99], v[32:33], off offset:384
	v_pk_mul_f32 v[32:33], v[80:81], v[94:95] op_sel_hi:[1,0]
	v_pk_mul_f32 v[34:35], v[82:83], v[94:95] op_sel_hi:[1,0]
	v_pk_fma_f32 v[32:33], v[16:17], v[32:33], v[20:21]
	v_pk_fma_f32 v[34:35], v[18:19], v[34:35], v[22:23]
	v_cvt_pk_bf16_f32 v32, v32, v33
	v_cvt_pk_bf16_f32 v33, v34, v35
	global_store_dwordx2 v[100:101], v[32:33], off offset:384
	v_pk_mul_f32 v[32:33], v[72:73], v[94:95] op_sel_hi:[1,0]
	v_pk_mul_f32 v[34:35], v[74:75], v[94:95] op_sel_hi:[1,0]
	v_pk_fma_f32 v[32:33], v[32:33], v[24:25], v[28:29]
	v_pk_fma_f32 v[34:35], v[34:35], v[26:27], v[30:31]
	v_cvt_pk_bf16_f32 v32, v32, v33
	v_cvt_pk_bf16_f32 v33, v34, v35
	global_store_dwordx2 v[102:103], v[32:33], off offset:384
	v_lshl_add_u64 v[32:33], s[8:9], 0, v[88:89]
	global_load_dwordx4 v[76:79], v[32:33], off nt
	global_load_dwordx4 v[68:71], v[32:33], off offset:1024 nt
	global_load_dwordx4 v[52:55], v[32:33], off offset:3072 nt
	global_load_dwordx4 v[60:63], v[32:33], off offset:2048 nt
	s_or_b32 s0, s6, 5
	s_ashr_i32 s1, s0, 31
	s_lshl_b64 s[0:1], s[0:1], 12
	s_add_u32 s0, s36, s0
	s_addc_u32 s1, s37, s1
	v_lshl_add_u64 v[44:45], s[0:1], 0, v[88:89]
	global_load_dwordx4 v[48:51], v[44:45], off nt
	global_load_dwordx4 v[40:43], v[44:45], off offset:1024 nt
	global_load_dwordx4 v[36:39], v[44:45], off offset:2048 nt
	global_load_dwordx4 v[32:35], v[44:45], off offset:3072 nt
	s_or_b32 s0, s6, 6
	s_ashr_i32 s1, s0, 31
	s_lshl_b64 s[0:1], s[0:1], 12
	s_add_u32 s0, s36, s0
	s_addc_u32 s1, s37, s1
	s_or_b32 s4, s6, 7
	s_ashr_i32 s5, s4, 31
	s_waitcnt vmcnt(7)
	v_pk_mul_f32 v[44:45], v[78:79], v[78:79]
	v_pk_mul_f32 v[46:47], v[76:77], v[76:77]
	s_nop 0
	v_pk_mov_b32 v[56:57], v[46:47], v[44:45] op_sel:[1,0]
	v_mov_b32_e32 v47, v45
	v_pk_add_f32 v[44:45], v[56:57], v[46:47]
	s_waitcnt vmcnt(6)
	v_pk_mul_f32 v[46:47], v[70:71], v[70:71]
	v_pk_mul_f32 v[56:57], v[68:69], v[68:69]
	v_pk_add_f32 v[44:45], v[44:45], v[44:45] op_sel:[0,1] op_sel_hi:[1,0]
	v_pk_mov_b32 v[58:59], v[56:57], v[46:47] op_sel:[1,0]
	v_mov_b32_e32 v57, v47
	v_pk_add_f32 v[46:47], v[58:59], v[56:57]
	s_waitcnt vmcnt(5)
	v_mul_f32_e32 v56, v52, v52
	v_mul_f32_e32 v57, v53, v53
	v_pk_add_f32 v[46:47], v[46:47], v[46:47] op_sel:[0,1] op_sel_hi:[1,0]
	v_mov_b32_e32 v45, v56
	v_mov_b32_e32 v47, v57
	v_pk_add_f32 v[44:45], v[44:45], v[46:47]
	s_waitcnt vmcnt(4)
	v_mul_f32_e32 v46, v61, v61
	v_mul_f32_e32 v56, v63, v63
	v_mul_f32_e32 v58, v54, v54
	v_mul_f32_e32 v59, v55, v55
	v_pk_fma_f32 v[46:47], v[60:61], v[60:61], v[46:47] op_sel_hi:[1,1,0]
	v_pk_fma_f32 v[56:57], v[62:63], v[62:63], v[56:57] op_sel_hi:[1,1,0]
	v_mov_b32_e32 v47, v58
	v_mov_b32_e32 v57, v59
	v_pk_add_f32 v[46:47], v[46:47], v[56:57]
	s_nop 0
	v_pk_add_f32 v[44:45], v[44:45], v[46:47]
	s_nop 0
	v_add_f32_e32 v44, v44, v45
	s_waitcnt lgkmcnt(0)
	s_nop 1
	v_add_f32_dpp v44, v44, v44 quad_perm:[1,0,3,2] row_mask:0xf bank_mask:0xf
	s_waitcnt lgkmcnt(0)
	s_nop 1
	v_add_f32_dpp v44, v44, v44 quad_perm:[2,3,0,1] row_mask:0xf bank_mask:0xf
	s_waitcnt lgkmcnt(0)
	s_nop 1
	v_mov_b32_dpp v45, v44 row_shl:4 row_mask:0xf bank_mask:0x5
	v_mov_b32_dpp v45, v44 row_shr:4 row_mask:0xf bank_mask:0xa
	v_add_f32_e32 v46, v44, v45
	v_lshl_add_u64 v[44:45], s[0:1], 0, v[88:89]
	global_load_dwordx4 v[84:87], v[44:45], off nt
	global_load_dwordx4 v[80:83], v[44:45], off offset:1024 nt
	s_lshl_b64 s[0:1], s[4:5], 12
	s_add_u32 s0, s36, s0
	s_addc_u32 s1, s37, s1
	v_lshl_add_u64 v[92:93], s[0:1], 0, v[88:89]
	s_waitcnt lgkmcnt(0)
	s_nop 1
	v_mov_b32_dpp v47, v46 row_shl:8 row_mask:0xf bank_mask:0x3
	v_mov_b32_dpp v47, v46 row_shr:8 row_mask:0xf bank_mask:0xc
	v_add_f32_e32 v46, v46, v47
	global_load_dwordx4 v[72:75], v[44:45], off offset:2048 nt
	global_load_dwordx4 v[64:67], v[44:45], off offset:3072 nt
	s_waitcnt lgkmcnt(0)
	s_nop 1
	v_readlane_b32 s98, v46, 0
	v_readlane_b32 s99, v46, 16
	v_readlane_b32 s100, v46, 32
	v_readlane_b32 s101, v46, 48
	s_nop 1
	v_mov_b32_e32 v47, s99
	v_add_f32_e32 v47, s98, v47
	v_mov_b32_e32 v90, s101
	v_add_f32_e32 v90, s100, v90
	v_add_f32_e32 v90, v47, v90
	global_load_dwordx4 v[56:59], v[92:93], off nt
	global_load_dwordx4 v[44:47], v[92:93], off offset:1024 nt
	s_waitcnt lgkmcnt(0)
	v_mov_b32_e32 v88, v90
	v_fmamk_f32 v88, v88, 0x3a800000, v104
	v_mul_f32_e32 v89, 0x4f800000, v88
	v_cmp_gt_f32_e32 vcc, s3, v88
	s_waitcnt vmcnt(9)
	v_pk_mul_f32 v[90:91], v[48:49], v[48:49]
	s_waitcnt vmcnt(4)
	v_pk_mul_f32 v[116:117], v[80:81], v[80:81]
	v_cndmask_b32_e32 v114, v88, v89, vcc
	v_pk_mul_f32 v[88:89], v[50:51], v[50:51]
	v_sqrt_f32_e32 v115, v114
	v_pk_mov_b32 v[94:95], v[90:91], v[88:89] op_sel:[1,0]
	v_mov_b32_e32 v91, v89
	v_pk_add_f32 v[88:89], v[94:95], v[90:91]
	v_pk_mul_f32 v[90:91], v[42:43], v[42:43]
	v_pk_mul_f32 v[94:95], v[40:41], v[40:41]
	v_pk_add_f32 v[88:89], v[88:89], v[88:89] op_sel:[0,1] op_sel_hi:[1,0]
	v_pk_mov_b32 v[112:113], v[94:95], v[90:91] op_sel:[1,0]
	v_mov_b32_e32 v95, v91
	v_pk_add_f32 v[90:91], v[112:113], v[94:95]
	v_mul_f32_e32 v94, v32, v32
	v_mul_f32_e32 v95, v33, v33
	v_pk_add_f32 v[90:91], v[90:91], v[90:91] op_sel:[0,1] op_sel_hi:[1,0]
	v_mov_b32_e32 v89, v94
	v_mov_b32_e32 v91, v95
	v_pk_add_f32 v[88:89], v[88:89], v[90:91]
	v_mul_f32_e32 v90, v37, v37
	v_mul_f32_e32 v94, v39, v39
	v_mul_f32_e32 v112, v34, v34
	v_mul_f32_e32 v113, v35, v35
	v_pk_fma_f32 v[90:91], v[36:37], v[36:37], v[90:91] op_sel_hi:[1,1,0]
	v_pk_fma_f32 v[94:95], v[38:39], v[38:39], v[94:95] op_sel_hi:[1,1,0]
	v_mov_b32_e32 v91, v112
	v_mov_b32_e32 v95, v113
	v_pk_add_f32 v[90:91], v[90:91], v[94:95]
	s_nop 0
	v_pk_add_f32 v[88:89], v[88:89], v[90:91]
	v_add_u32_e32 v90, -1, v115
	v_add_f32_e32 v88, v88, v89
	v_fma_f32 v91, -v90, v115, v114
	v_cmp_ge_f32_e64 s[0:1], 0, v91
	v_add_u32_e32 v91, 1, v115
	v_fma_f32 v94, -v91, v115, v114
	s_waitcnt lgkmcnt(0)
	s_nop 1
	v_add_f32_dpp v88, v88, v88 quad_perm:[1,0,3,2] row_mask:0xf bank_mask:0xf
	v_cndmask_b32_e64 v90, v115, v90, s[0:1]
	v_cmp_lt_f32_e64 s[0:1], 0, v94
	s_waitcnt lgkmcnt(0)
	s_nop 1
	v_add_f32_dpp v88, v88, v88 quad_perm:[2,3,0,1] row_mask:0xf bank_mask:0xf
	v_cndmask_b32_e64 v90, v90, v91, s[0:1]
	v_mul_f32_e32 v91, 0x37800000, v90
	v_cndmask_b32_e32 v90, v90, v91, vcc
	v_cmp_class_f32_e32 vcc, v114, v111
	s_waitcnt lgkmcnt(0)
	s_nop 1
	v_mov_b32_dpp v89, v88 row_shl:4 row_mask:0xf bank_mask:0x5
	v_mov_b32_dpp v89, v88 row_shr:4 row_mask:0xf bank_mask:0xa
	v_add_f32_e32 v94, v88, v89
	v_cndmask_b32_e32 v120, v90, v114, vcc
	v_div_scale_f32 v121, s[0:1], v120, v120, 1.0
	v_rcp_f32_e32 v122, v121
	s_waitcnt lgkmcnt(0)
	s_nop 1
	v_mov_b32_dpp v95, v94 row_shl:8 row_mask:0xf bank_mask:0x3
	v_mov_b32_dpp v95, v94 row_shr:8 row_mask:0xf bank_mask:0xc
	v_add_f32_e32 v94, v94, v95
	global_load_dwordx4 v[88:91], v[92:93], off offset:3072 nt
	v_fma_f32 v112, -v121, v122, 1.0
	v_fmac_f32_e32 v122, v112, v122
	v_pk_mul_f32 v[112:113], v[84:85], v[84:85]
	s_waitcnt lgkmcnt(0)
	s_nop 1
	v_readlane_b32 s98, v94, 0
	v_readlane_b32 s99, v94, 16
	v_readlane_b32 s100, v94, 32
	v_readlane_b32 s101, v94, 48
	s_nop 1
	v_mov_b32_e32 v95, s99
	v_add_f32_e32 v95, s98, v95
	v_mov_b32_e32 v124, s101
	v_add_f32_e32 v124, s100, v124
	v_add_f32_e32 v124, v95, v124
	v_pk_mul_f32 v[94:95], v[86:87], v[86:87]
	v_pk_mov_b32 v[114:115], v[112:113], v[94:95] op_sel:[1,0]
	v_mov_b32_e32 v113, v95
	global_load_dwordx4 v[92:95], v[92:93], off offset:2048 nt
	v_pk_add_f32 v[112:113], v[114:115], v[112:113]
	v_pk_mul_f32 v[114:115], v[82:83], v[82:83]
	v_pk_add_f32 v[112:113], v[112:113], v[112:113] op_sel:[0,1] op_sel_hi:[1,0]
	v_pk_mov_b32 v[118:119], v[116:117], v[114:115] op_sel:[1,0]
	s_waitcnt lgkmcnt(0)
	v_mov_b32_e32 v114, v124
	v_fmamk_f32 v114, v114, 0x3a800000, v104
	v_mov_b32_e32 v117, v115
	v_mul_f32_e32 v115, 0x4f800000, v114
	v_cmp_gt_f32_e64 s[0:1], s3, v114
	v_div_scale_f32 v123, vcc, 1.0, v120, 1.0
	s_nop 0
	v_cndmask_b32_e64 v124, v114, v115, s[0:1]
	v_pk_add_f32 v[114:115], v[118:119], v[116:117]
	s_waitcnt vmcnt(4)
	v_mul_f32_e32 v116, v64, v64
	v_mul_f32_e32 v117, v65, v65
	v_pk_add_f32 v[114:115], v[114:115], v[114:115] op_sel:[0,1] op_sel_hi:[1,0]
	v_mov_b32_e32 v113, v116
	v_mov_b32_e32 v115, v117
	v_pk_add_f32 v[112:113], v[112:113], v[114:115]
	v_mul_f32_e32 v114, v73, v73
	v_mul_f32_e32 v116, v75, v75
	v_mul_f32_e32 v118, v66, v66
	v_mul_f32_e32 v119, v67, v67
	v_pk_fma_f32 v[114:115], v[72:73], v[72:73], v[114:115] op_sel_hi:[1,1,0]
	v_pk_fma_f32 v[116:117], v[74:75], v[74:75], v[116:117] op_sel_hi:[1,1,0]
	v_mov_b32_e32 v115, v118
	v_mov_b32_e32 v117, v119
	v_pk_add_f32 v[114:115], v[114:115], v[116:117]
	v_sqrt_f32_e32 v118, v124
	v_pk_add_f32 v[112:113], v[112:113], v[114:115]
	v_mul_f32_e32 v126, v123, v122
	v_add_f32_e32 v112, v112, v113
	v_add_u32_e32 v115, -1, v118
	v_fma_f32 v116, -v115, v118, v124
	v_cmp_ge_f32_e64 s[4:5], 0, v116
	v_add_u32_e32 v116, 1, v118
	s_waitcnt lgkmcnt(0)
	s_nop 1
	v_add_f32_dpp v112, v112, v112 quad_perm:[1,0,3,2] row_mask:0xf bank_mask:0xf
	v_fma_f32 v117, -v116, v118, v124
	v_cndmask_b32_e64 v115, v118, v115, s[4:5]
	v_cmp_lt_f32_e64 s[4:5], 0, v117
	v_fma_f32 v127, -v121, v126, v123
	s_waitcnt lgkmcnt(0)
	s_nop 1
	v_add_f32_dpp v112, v112, v112 quad_perm:[2,3,0,1] row_mask:0xf bank_mask:0xf
	v_cndmask_b32_e64 v115, v115, v116, s[4:5]
	v_mul_f32_e32 v116, 0x37800000, v115
	v_fmac_f32_e32 v126, v127, v122
	v_cndmask_b32_e64 v115, v115, v116, s[0:1]
	s_waitcnt lgkmcnt(0)
	s_nop 1
	v_mov_b32_dpp v113, v112 row_shl:4 row_mask:0xf bank_mask:0x5
	v_mov_b32_dpp v113, v112 row_shr:4 row_mask:0xf bank_mask:0xa
	v_add_f32_e32 v112, v112, v113
	v_cmp_class_f32_e64 s[0:1], v124, v111
	v_fma_f32 v114, -v121, v126, v123
	v_div_fmas_f32 v122, v114, v122, v126
	v_cndmask_b32_e64 v121, v115, v124, s[0:1]
	v_div_scale_f32 v123, s[0:1], v121, v121, 1.0
	s_waitcnt lgkmcnt(0)
	s_nop 1
	v_mov_b32_dpp v113, v112 row_shl:8 row_mask:0xf bank_mask:0x3
	v_mov_b32_dpp v113, v112 row_shr:8 row_mask:0xf bank_mask:0xc
	v_add_f32_e32 v112, v112, v113
	v_rcp_f32_e32 v124, v123
	v_fma_f32 v114, -v123, v124, 1.0
	v_fmac_f32_e32 v124, v114, v124
	s_waitcnt lgkmcnt(0)
	s_nop 1
	v_readlane_b32 s98, v112, 0
	v_readlane_b32 s99, v112, 16
	v_readlane_b32 s100, v112, 32
	v_readlane_b32 s101, v112, 48
	s_nop 1
	v_mov_b32_e32 v113, s99
	v_add_f32_e32 v113, s98, v113
	v_mov_b32_e32 v125, s101
	v_add_f32_e32 v125, s100, v125
	v_add_f32_e32 v125, v113, v125
	s_waitcnt vmcnt(3)
	v_pk_mul_f32 v[112:113], v[58:59], v[58:59]
	v_pk_mul_f32 v[114:115], v[56:57], v[56:57]
	s_nop 0
	v_pk_mov_b32 v[116:117], v[114:115], v[112:113] op_sel:[1,0]
	v_mov_b32_e32 v115, v113
	v_pk_add_f32 v[112:113], v[116:117], v[114:115]
	s_waitcnt vmcnt(2)
	v_pk_mul_f32 v[114:115], v[46:47], v[46:47]
	v_pk_mul_f32 v[116:117], v[44:45], v[44:45]
	v_pk_add_f32 v[112:113], v[112:113], v[112:113] op_sel:[0,1] op_sel_hi:[1,0]
	v_pk_mov_b32 v[118:119], v[116:117], v[114:115] op_sel:[1,0]
	v_mov_b32_e32 v117, v115
	v_pk_add_f32 v[114:115], v[118:119], v[116:117]
	s_waitcnt vmcnt(1)
	v_mul_f32_e32 v116, v88, v88
	v_mul_f32_e32 v117, v89, v89
	v_pk_add_f32 v[114:115], v[114:115], v[114:115] op_sel:[0,1] op_sel_hi:[1,0]
	v_mov_b32_e32 v113, v116
	v_mov_b32_e32 v115, v117
	v_pk_add_f32 v[112:113], v[112:113], v[114:115]
	s_waitcnt vmcnt(0)
	v_mul_f32_e32 v114, v93, v93
	v_mul_f32_e32 v116, v90, v90
	v_pk_fma_f32 v[114:115], v[92:93], v[92:93], v[114:115] op_sel_hi:[1,1,0]
	v_div_fixup_f32 v118, v122, v120, 1.0
	v_mov_b32_e32 v115, v116
	v_mul_f32_e32 v116, v95, v95
	v_pk_fma_f32 v[116:117], v[94:95], v[94:95], v[116:117] op_sel_hi:[1,1,0]
	s_nop 0
	v_mul_f32_e32 v117, v91, v91
	v_pk_add_f32 v[114:115], v[114:115], v[116:117]
	v_pk_add_f32 v[112:113], v[112:113], v[114:115]
	v_div_scale_f32 v117, vcc, 1.0, v121, 1.0
	v_add_f32_e32 v112, v112, v113
	s_waitcnt lgkmcnt(0)
	v_mov_b32_e32 v116, v125
	v_fmamk_f32 v116, v116, 0x3a800000, v104
	v_mul_f32_e32 v119, 0x4f800000, v116
	v_cmp_gt_f32_e64 s[0:1], s3, v116
	s_waitcnt lgkmcnt(0)
	s_nop 1
	v_add_f32_dpp v110, v112, v112 quad_perm:[1,0,3,2] row_mask:0xf bank_mask:0xf
	v_cndmask_b32_e64 v116, v116, v119, s[0:1]
	v_sqrt_f32_e32 v119, v116
	v_mul_f32_e32 v114, v117, v124
	v_fma_f32 v115, -v123, v114, v117
	s_waitcnt lgkmcnt(0)
	s_nop 1
	v_add_f32_dpp v109, v110, v110 quad_perm:[2,3,0,1] row_mask:0xf bank_mask:0xf
	v_fmac_f32_e32 v114, v115, v124
	v_add_u32_e32 v115, -1, v119
	v_fma_f32 v113, -v123, v114, v117
	v_fma_f32 v117, -v115, v119, v116
	s_waitcnt lgkmcnt(0)
	s_nop 1
	v_mov_b32_dpp v108, v109 row_shl:4 row_mask:0xf bank_mask:0x5
	v_mov_b32_dpp v108, v109 row_shr:4 row_mask:0xf bank_mask:0xa
	v_add_f32_e32 v108, v109, v108
	v_cmp_ge_f32_e64 s[4:5], 0, v117
	v_pk_mul_f32 v[76:77], v[76:77], v[118:119] op_sel_hi:[1,0]
	v_pk_mul_f32 v[78:79], v[78:79], v[118:119] op_sel_hi:[1,0]
	v_cndmask_b32_e64 v112, v119, v115, s[4:5]
	s_waitcnt lgkmcnt(0)
	s_nop 1
	v_mov_b32_dpp v107, v108 row_shl:8 row_mask:0xf bank_mask:0x3
	v_mov_b32_dpp v107, v108 row_shr:8 row_mask:0xf bank_mask:0xc
	v_add_f32_e32 v107, v108, v107
	v_add_u32_e32 v115, 1, v119
	v_fma_f32 v117, -v115, v119, v116
	v_cmp_lt_f32_e64 s[4:5], 0, v117
	v_div_fmas_f32 v106, v113, v124, v114
	s_waitcnt lgkmcnt(0)
	s_nop 1
	v_readlane_b32 s98, v107, 0
	v_readlane_b32 s99, v107, 16
	v_readlane_b32 s100, v107, 32
	v_readlane_b32 s101, v107, 48
	s_nop 1
	v_mov_b32_e32 v108, s99
	v_add_f32_e32 v108, s98, v108
	v_mov_b32_e32 v107, s101
	v_add_f32_e32 v107, s100, v107
	v_add_f32_e32 v107, v108, v107
	v_cndmask_b32_e64 v110, v112, v115, s[4:5]
	v_mul_f32_e32 v112, 0x37800000, v110
	v_cndmask_b32_e64 v110, v110, v112, s[0:1]
	v_cmp_class_f32_e64 s[0:1], v116, v111
	v_div_fixup_f32 v106, v106, v121, 1.0
	v_pk_mul_f32 v[68:69], v[68:69], v[118:119] op_sel_hi:[1,0]
	v_cndmask_b32_e64 v109, v110, v116, s[0:1]
	v_div_scale_f32 v110, s[0:1], v109, v109, 1.0
	v_rcp_f32_e32 v112, v110
	s_waitcnt lgkmcnt(0)
	v_mov_b32_e32 v105, v107
	v_fmac_f32_e32 v104, 0x3a800000, v105
	v_mul_f32_e32 v105, 0x4f800000, v104
	v_cmp_gt_f32_e64 s[0:1], s3, v104
	v_fma_f32 v113, -v110, v112, 1.0
	v_fmac_f32_e32 v112, v113, v112
	v_cndmask_b32_e64 v104, v104, v105, s[0:1]
	v_div_scale_f32 v108, vcc, 1.0, v109, 1.0
	v_sqrt_f32_e32 v105, v104
	v_mul_f32_e32 v113, v108, v112
	v_fma_f32 v107, -v110, v113, v108
	v_fmac_f32_e32 v113, v107, v112
	v_fma_f32 v107, -v110, v113, v108
	v_add_u32_e32 v108, -1, v105
	v_fma_f32 v110, -v108, v105, v104
	v_cmp_ge_f32_e64 s[4:5], 0, v110
	v_add_u32_e32 v110, 1, v105
	v_pk_mul_f32 v[70:71], v[70:71], v[118:119] op_sel_hi:[1,0]
	v_cndmask_b32_e64 v108, v105, v108, s[4:5]
	v_fma_f32 v105, -v110, v105, v104
	v_cmp_lt_f32_e64 s[4:5], 0, v105
	v_pk_mul_f32 v[60:61], v[60:61], v[118:119] op_sel_hi:[1,0]
	v_pk_mul_f32 v[62:63], v[62:63], v[118:119] op_sel_hi:[1,0]
	v_cndmask_b32_e64 v105, v108, v110, s[4:5]
	v_mul_f32_e32 v108, 0x37800000, v105
	v_cndmask_b32_e64 v105, v105, v108, s[0:1]
	v_cmp_class_f32_e64 s[0:1], v104, v111
	v_pk_mul_f32 v[52:53], v[52:53], v[118:119] op_sel_hi:[1,0]
	v_pk_mul_f32 v[54:55], v[54:55], v[118:119] op_sel_hi:[1,0]
	v_cndmask_b32_e64 v105, v105, v104, s[0:1]
	v_div_scale_f32 v108, s[0:1], v105, v105, 1.0
	v_rcp_f32_e32 v110, v108
	v_div_fmas_f32 v104, v107, v112, v113
	v_div_fixup_f32 v104, v104, v109, 1.0
	v_pk_fma_f32 v[78:79], v[2:3], v[78:79], v[6:7]
	v_fma_f32 v107, -v108, v110, 1.0
	v_fmac_f32_e32 v110, v107, v110
	v_div_scale_f32 v107, vcc, 1.0, v105, 1.0
	v_mul_f32_e32 v109, v107, v110
	v_fma_f32 v111, -v108, v109, v107
	v_fmac_f32_e32 v109, v111, v110
	v_fma_f32 v107, -v108, v109, v107
	v_div_fmas_f32 v107, v107, v110, v109
	v_pk_mul_f32 v[48:49], v[48:49], v[106:107] op_sel_hi:[1,0]
	v_pk_mul_f32 v[50:51], v[50:51], v[106:107] op_sel_hi:[1,0]
	v_pk_mul_f32 v[40:41], v[40:41], v[106:107] op_sel_hi:[1,0]
	v_pk_mul_f32 v[42:43], v[42:43], v[106:107] op_sel_hi:[1,0]
	v_pk_mul_f32 v[36:37], v[36:37], v[106:107] op_sel_hi:[1,0]
	v_pk_mul_f32 v[38:39], v[38:39], v[106:107] op_sel_hi:[1,0]
	v_pk_mul_f32 v[32:33], v[32:33], v[106:107] op_sel_hi:[1,0]
	v_pk_mul_f32 v[34:35], v[34:35], v[106:107] op_sel_hi:[1,0]
	v_pk_fma_f32 v[76:77], v[0:1], v[76:77], v[4:5]
	v_pk_fma_f32 v[70:71], v[10:11], v[70:71], v[14:15]
	v_pk_fma_f32 v[68:69], v[8:9], v[68:69], v[12:13]
	v_pk_fma_f32 v[62:63], v[18:19], v[62:63], v[22:23]
	v_pk_fma_f32 v[60:61], v[16:17], v[60:61], v[20:21]
	v_pk_fma_f32 v[54:55], v[26:27], v[54:55], v[30:31]
	v_pk_fma_f32 v[52:53], v[24:25], v[52:53], v[28:29]
	v_pk_fma_f32 v[50:51], v[2:3], v[50:51], v[6:7]
	v_pk_fma_f32 v[48:49], v[0:1], v[48:49], v[4:5]
	v_pk_fma_f32 v[42:43], v[10:11], v[42:43], v[14:15]
	v_pk_fma_f32 v[40:41], v[8:9], v[40:41], v[12:13]
	v_pk_fma_f32 v[38:39], v[18:19], v[38:39], v[22:23]
	v_pk_fma_f32 v[36:37], v[16:17], v[36:37], v[20:21]
	v_pk_fma_f32 v[34:35], v[26:27], v[34:35], v[30:31]
	v_pk_fma_f32 v[32:33], v[24:25], v[32:33], v[28:29]
	v_cvt_pk_bf16_f32 v76, v76, v77
	v_cvt_pk_bf16_f32 v77, v78, v79
	v_cvt_pk_bf16_f32 v68, v68, v69
	v_cvt_pk_bf16_f32 v69, v70, v71
	v_cvt_pk_bf16_f32 v60, v60, v61
	v_cvt_pk_bf16_f32 v61, v62, v63
	v_cvt_pk_bf16_f32 v52, v52, v53
	v_cvt_pk_bf16_f32 v53, v54, v55
	v_cvt_pk_bf16_f32 v48, v48, v49
	v_cvt_pk_bf16_f32 v49, v50, v51
	v_cvt_pk_bf16_f32 v40, v40, v41
	v_cvt_pk_bf16_f32 v41, v42, v43
	v_cvt_pk_bf16_f32 v36, v36, v37
	v_cvt_pk_bf16_f32 v37, v38, v39
	v_cvt_pk_bf16_f32 v32, v32, v33
	v_cvt_pk_bf16_f32 v33, v34, v35
	global_store_dwordx2 v[96:97], v[76:77], off offset:512
	global_store_dwordx2 v[98:99], v[68:69], off offset:512
	global_store_dwordx2 v[100:101], v[60:61], off offset:512
	global_store_dwordx2 v[102:103], v[52:53], off offset:512
	global_store_dwordx2 v[96:97], v[48:49], off offset:640
	global_store_dwordx2 v[98:99], v[40:41], off offset:640
	global_store_dwordx2 v[100:101], v[36:37], off offset:640
	global_store_dwordx2 v[102:103], v[32:33], off offset:640
	v_pk_mul_f32 v[32:33], v[84:85], v[104:105] op_sel_hi:[1,0]
	v_pk_mul_f32 v[34:35], v[86:87], v[104:105] op_sel_hi:[1,0]
	v_pk_fma_f32 v[32:33], v[0:1], v[32:33], v[4:5]
	v_pk_fma_f32 v[34:35], v[2:3], v[34:35], v[6:7]
	v_cvt_pk_bf16_f32 v32, v32, v33
	v_cvt_pk_bf16_f32 v33, v34, v35
	global_store_dwordx2 v[96:97], v[32:33], off offset:768
	v_pk_mul_f32 v[32:33], v[80:81], v[104:105] op_sel_hi:[1,0]
	v_pk_mul_f32 v[34:35], v[82:83], v[104:105] op_sel_hi:[1,0]
	v_pk_fma_f32 v[32:33], v[8:9], v[32:33], v[12:13]
	v_pk_fma_f32 v[34:35], v[10:11], v[34:35], v[14:15]
	v_cvt_pk_bf16_f32 v32, v32, v33
	v_cvt_pk_bf16_f32 v33, v34, v35
	global_store_dwordx2 v[98:99], v[32:33], off offset:768
	v_pk_mul_f32 v[32:33], v[72:73], v[104:105] op_sel_hi:[1,0]
	v_pk_mul_f32 v[34:35], v[74:75], v[104:105] op_sel_hi:[1,0]
	v_pk_fma_f32 v[32:33], v[16:17], v[32:33], v[20:21]
	v_pk_fma_f32 v[34:35], v[18:19], v[34:35], v[22:23]
	v_cvt_pk_bf16_f32 v32, v32, v33
	v_cvt_pk_bf16_f32 v33, v34, v35
	global_store_dwordx2 v[100:101], v[32:33], off offset:768
	v_pk_mul_f32 v[32:33], v[64:65], v[104:105] op_sel_hi:[1,0]
	v_pk_mul_f32 v[34:35], v[66:67], v[104:105] op_sel_hi:[1,0]
	v_pk_fma_f32 v[32:33], v[24:25], v[32:33], v[28:29]
	v_pk_fma_f32 v[34:35], v[26:27], v[34:35], v[30:31]
	v_div_fixup_f32 v108, v107, v105, 1.0
	v_cvt_pk_bf16_f32 v32, v32, v33
	v_cvt_pk_bf16_f32 v33, v34, v35
	global_store_dwordx2 v[102:103], v[32:33], off offset:768
	v_pk_mul_f32 v[32:33], v[56:57], v[108:109] op_sel_hi:[1,0]
	v_pk_mul_f32 v[34:35], v[58:59], v[108:109] op_sel_hi:[1,0]
	v_pk_fma_f32 v[0:1], v[0:1], v[32:33], v[4:5]
	v_pk_fma_f32 v[2:3], v[2:3], v[34:35], v[6:7]
	v_cvt_pk_bf16_f32 v0, v0, v1
	v_cvt_pk_bf16_f32 v1, v2, v3
	global_store_dwordx2 v[96:97], v[0:1], off offset:896
	v_pk_mul_f32 v[0:1], v[44:45], v[108:109] op_sel_hi:[1,0]
	v_pk_mul_f32 v[2:3], v[46:47], v[108:109] op_sel_hi:[1,0]
	v_pk_fma_f32 v[0:1], v[8:9], v[0:1], v[12:13]
	v_pk_fma_f32 v[2:3], v[10:11], v[2:3], v[14:15]
	v_cvt_pk_bf16_f32 v0, v0, v1
	v_cvt_pk_bf16_f32 v1, v2, v3
	global_store_dwordx2 v[98:99], v[0:1], off offset:896
	v_pk_mul_f32 v[0:1], v[92:93], v[108:109] op_sel_hi:[1,0]
	v_pk_mul_f32 v[2:3], v[94:95], v[108:109] op_sel_hi:[1,0]
	v_pk_fma_f32 v[0:1], v[16:17], v[0:1], v[20:21]
	v_pk_fma_f32 v[2:3], v[18:19], v[2:3], v[22:23]
	v_cvt_pk_bf16_f32 v0, v0, v1
	v_cvt_pk_bf16_f32 v1, v2, v3
	global_store_dwordx2 v[100:101], v[0:1], off offset:896
	v_pk_mul_f32 v[0:1], v[88:89], v[108:109] op_sel_hi:[1,0]
	v_pk_mul_f32 v[2:3], v[90:91], v[108:109] op_sel_hi:[1,0]
	v_pk_fma_f32 v[0:1], v[24:25], v[0:1], v[28:29]
	v_pk_fma_f32 v[2:3], v[26:27], v[2:3], v[30:31]
	v_cvt_pk_bf16_f32 v0, v0, v1
	v_cvt_pk_bf16_f32 v1, v2, v3
	global_store_dwordx2 v[102:103], v[0:1], off offset:896
